# conversion split plus non-temporal hint on the once-read f32 KV-cache loads of the sample units (cache policy lever)
# speedup vs baseline: 1.0052x; 1.0052x over previous
.LBB0_820:
	s_and_b64 vcc, exec, s[0:1]
	s_cbranch_vccz .LBB0_750
	s_waitcnt lgkmcnt(0)
	s_add_u32 s0, s12, s78
	s_addc_u32 s1, s13, s79
	s_add_u32 s6, s0, s86
	s_addc_u32 s7, s1, 0
	s_add_u32 s2, s14, s78
	s_addc_u32 s8, s15, s79
	s_add_u32 s12, s2, s86
	s_addc_u32 s13, s8, 0
	s_add_i32 s47, s47, -4
	v_lshlrev_b32_e32 v6, 10, v1
	v_and_b32_e32 v4, 7, v1
	s_lshl_b32 s9, s47, 5
	v_and_b32_e32 v6, 0xe000, v6
	v_lshlrev_b32_e32 v5, 2, v4
	v_add_u32_e32 v6, s9, v6
	v_or_b32_e32 v6, v6, v5
	s_lshl_b32 s14, s47, 3
	v_lshrrev_b32_e32 v8, 3, v163
	v_lshlrev_b32_e32 v132, 2, v6
	v_or_b32_e32 v6, s14, v4
	v_bitop3_b32 v4, s14, 15, v4 bitop3:0xc8
	v_lshl_add_u32 v2, v8, 10, s9
	v_cmp_eq_u32_e32 vcc, 2, v4
	v_or_b32_e32 v2, v2, v5
	v_lshlrev_b32_e32 v2, 2, v2
	v_cndmask_b32_e64 v7, 0, -1, vcc
	v_cmp_ne_u32_e32 vcc, 1, v4
	v_mov_b32_e32 v133, v3
	v_lshl_add_u64 v[136:137], s[6:7], 0, v[2:3]
	v_cndmask_b32_e32 v4, 1, v7, vcc
	v_add_u32_e32 v66, v4, v6
	v_or_b32_e32 v4, s9, v5
	v_mul_lo_u32 v138, v4, s20
	v_add_co_u32_e32 v4, vcc, s90, v136
	v_lshl_add_u64 v[134:135], s[12:13], 0, v[132:133]
	s_nop 0
	v_addc_co_u32_e32 v5, vcc, 0, v137, vcc
	global_load_dwordx4 v[16:19], v2, s[6:7] nt
	global_load_dwordx4 v[20:23], v[4:5], off nt
	v_add_co_u32_e32 v4, vcc, s37, v136
	s_movk_i32 s6, 0x2000
	s_nop 0
	v_addc_co_u32_e32 v5, vcc, 0, v137, vcc
	v_add_co_u32_e32 v6, vcc, s38, v136
	v_lshrrev_b32_e32 v1, 1, v1
	s_nop 0
	v_addc_co_u32_e32 v7, vcc, 0, v137, vcc
	global_load_dwordx4 v[24:27], v[4:5], off nt
	global_load_dwordx4 v[28:31], v[6:7], off nt
	v_add_co_u32_e32 v4, vcc, s53, v136
	v_and_b32_e32 v139, 16, v1
	s_nop 0
	v_addc_co_u32_e32 v5, vcc, 0, v137, vcc
	v_add_co_u32_e32 v6, vcc, s55, v136
	v_lshrrev_b32_e32 v1, 1, v163
	s_nop 0
	v_addc_co_u32_e32 v7, vcc, 0, v137, vcc
	global_load_dwordx4 v[32:35], v[4:5], off nt
	global_load_dwordx4 v[36:39], v[6:7], off nt
	v_add_co_u32_e32 v4, vcc, s91, v136
	v_and_b32_e32 v140, 12, v1
	s_nop 0
	v_addc_co_u32_e32 v5, vcc, 0, v137, vcc
	v_add_co_u32_e32 v6, vcc, s93, v136
	v_mul_u32_u24_e32 v1, 0x90, v8
	s_nop 0
	v_addc_co_u32_e32 v7, vcc, 0, v137, vcc
	global_load_dwordx4 v[40:43], v[4:5], off nt
	global_load_dwordx4 v[44:47], v[6:7], off nt
	v_add_co_u32_e32 v4, vcc, s6, v134
	s_movk_i32 s6, 0x6000
	s_nop 0
	v_addc_co_u32_e32 v5, vcc, 0, v135, vcc
	v_add_co_u32_e32 v6, vcc, s33, v134
	v_lshl_add_u32 v1, v66, 2, v1
	s_nop 0
	v_addc_co_u32_e32 v7, vcc, 0, v135, vcc
	v_add_co_u32_e32 v64, vcc, s6, v134
	s_movk_i32 s6, 0x7000
	s_nop 0
	v_addc_co_u32_e32 v65, vcc, 0, v135, vcc
	v_add_co_u32_e32 v12, vcc, s6, v134
	s_mov_b32 s6, 0x40000
	s_nop 0
	v_addc_co_u32_e32 v13, vcc, 0, v135, vcc
	v_add_co_u32_e32 v66, vcc, s6, v136
	global_load_dwordx4 v[48:51], v132, s[12:13] nt
	global_load_dwordx4 v[52:55], v[4:5], off offset:-4096 nt
	v_addc_co_u32_e32 v67, vcc, 0, v137, vcc
	s_mov_b32 s6, 0x48000
	global_load_dwordx4 v[56:59], v[4:5], off nt
	global_load_dwordx4 v[60:63], v[6:7], off offset:-4096 nt
	v_add_co_u32_e32 v68, vcc, s6, v136
	global_load_dwordx4 v[4:7], v[6:7], off nt
	s_nop 0
	global_load_dwordx4 v[8:11], v[64:65], off offset:-4096 nt
	v_addc_co_u32_e32 v69, vcc, 0, v137, vcc
	global_load_dwordx4 v[12:15], v[12:13], off nt
	s_nop 0
	global_load_dwordx4 v[128:131], v[66:67], off nt
	global_load_dwordx4 v[124:127], v[68:69], off nt
	s_mov_b32 s6, 0x50000
	v_add_co_u32_e32 v66, vcc, s6, v136
	s_mov_b32 s6, 0x58000
	s_nop 0
	v_addc_co_u32_e32 v67, vcc, 0, v137, vcc
	v_add_co_u32_e32 v68, vcc, s6, v136
	s_mov_b32 s6, 0x60000
	s_nop 0
	v_addc_co_u32_e32 v69, vcc, 0, v137, vcc
	global_load_dwordx4 v[120:123], v[66:67], off nt
	global_load_dwordx4 v[116:119], v[68:69], off nt
	v_add_co_u32_e32 v66, vcc, s6, v136
	s_mov_b32 s6, 0x68000
	s_nop 0
	v_addc_co_u32_e32 v67, vcc, 0, v137, vcc
	v_add_co_u32_e32 v68, vcc, s6, v136
	s_mov_b32 s6, 0x70000
	s_nop 0
	v_addc_co_u32_e32 v69, vcc, 0, v137, vcc
	global_load_dwordx4 v[112:115], v[66:67], off nt
	global_load_dwordx4 v[108:111], v[68:69], off nt
	v_add_co_u32_e32 v66, vcc, s6, v136
	s_mov_b32 s6, 0x78000
	s_nop 0
	v_addc_co_u32_e32 v67, vcc, 0, v137, vcc
	v_add_co_u32_e32 v68, vcc, s6, v136
	s_mov_b32 s6, 0x41000
	s_nop 0
	v_addc_co_u32_e32 v69, vcc, 0, v137, vcc
	global_load_dwordx4 v[104:107], v[66:67], off nt
	global_load_dwordx4 v[100:103], v[68:69], off nt
	v_add_co_u32_e32 v68, vcc, s6, v134
	s_mov_b32 s6, 0x43000
	s_nop 0
	v_addc_co_u32_e32 v69, vcc, 0, v135, vcc
	global_load_dwordx4 v[64:67], v[64:65], off nt
	s_nop 0
	global_load_dwordx4 v[84:87], v[68:69], off offset:-4096 nt
	v_add_co_u32_e32 v70, vcc, s6, v134
	s_mov_b32 s6, 0x45000
	s_nop 0
	v_addc_co_u32_e32 v71, vcc, 0, v135, vcc
	global_load_dwordx4 v[88:91], v[68:69], off nt
	global_load_dwordx4 v[92:95], v[70:71], off offset:-4096 nt
	v_add_co_u32_e32 v72, vcc, s6, v134
	s_mov_b32 s6, 0x47000
	s_nop 0
	v_addc_co_u32_e32 v73, vcc, 0, v135, vcc
	global_load_dwordx4 v[96:99], v[70:71], off nt
	s_nop 0
	global_load_dwordx4 v[68:71], v[72:73], off offset:-4096 nt
	v_add_co_u32_e32 v76, vcc, s6, v134
	s_waitcnt vmcnt(28)
	v_mul_f32_e32 v16, 0x41800000, v16
	v_addc_co_u32_e32 v77, vcc, 0, v135, vcc
	global_load_dwordx4 v[80:83], v[72:73], off nt
	s_nop 0
	global_load_dwordx4 v[72:75], v[76:77], off offset:-4096 nt
	s_nop 0
	global_load_dwordx4 v[76:79], v[76:77], off nt
	v_mul_f32_e32 v17, 0x41800000, v17
	v_mov_b32_e32 v142, v3
	v_cvt_pk_fp8_f32 v142, v16, v17
	s_waitcnt vmcnt(30)
	v_mul_f32_e32 v16, 0x41800000, v20
	v_mul_f32_e32 v17, 0x41800000, v21
	v_mov_b32_e32 v20, v3
	v_cvt_pk_fp8_f32 v20, v16, v17
	v_mul_f32_e32 v16, 0x41800000, v22
	v_mul_f32_e32 v17, 0x41800000, v23
	v_mov_b32_e32 v21, v3
	v_cvt_pk_fp8_f32 v20, v16, v17 op_sel:[0,0,1]
	s_waitcnt vmcnt(29)
	v_mul_f32_e32 v16, 0x41800000, v24
	v_mul_f32_e32 v17, 0x41800000, v25
	v_cvt_pk_fp8_f32 v21, v16, v17
	s_waitcnt vmcnt(28)
	v_mul_f32_e32 v16, 0x41800000, v28
	v_mul_f32_e32 v17, 0x41800000, v29
	v_mov_b32_e32 v22, v3
	v_mul_f32_e32 v18, 0x41800000, v18
	v_mul_f32_e32 v19, 0x41800000, v19
	v_cvt_pk_fp8_f32 v22, v16, v17
	v_cvt_pk_fp8_f32 v142, v18, v19 op_sel:[0,0,1]
	v_mul_f32_e32 v18, 0x41800000, v26
	v_mul_f32_e32 v19, 0x41800000, v27
	v_cvt_pk_fp8_f32 v21, v18, v19 op_sel:[0,0,1]
	v_mul_f32_e32 v16, 0x41800000, v30
	v_mul_f32_e32 v17, 0x41800000, v31
	v_add_u32_e32 v141, 0, v1
	v_cvt_pk_fp8_f32 v22, v16, v17 op_sel:[0,0,1]
	ds_write_b32 v141, v142
	ds_write_b32 v141, v20 offset:1152
	ds_write_b32 v141, v21 offset:2304
	ds_write_b32 v141, v22 offset:3456
	s_waitcnt vmcnt(27)
	v_mul_f32_e32 v16, 0x41800000, v32
	v_mul_f32_e32 v17, 0x41800000, v33
	v_mov_b32_e32 v20, v3
	v_cvt_pk_fp8_f32 v20, v16, v17
	s_waitcnt vmcnt(26)
	v_mul_f32_e32 v16, 0x41800000, v36
	v_mul_f32_e32 v17, 0x41800000, v37
	v_mov_b32_e32 v21, v3
	v_cvt_pk_fp8_f32 v21, v16, v17
	v_mul_f32_e32 v16, 0x41800000, v38
	v_mul_f32_e32 v17, 0x41800000, v39
	v_mov_b32_e32 v22, v3
	v_cvt_pk_fp8_f32 v21, v16, v17 op_sel:[0,0,1]
	s_waitcnt vmcnt(25)
	v_mul_f32_e32 v16, 0x41800000, v40
	v_mul_f32_e32 v17, 0x41800000, v41
	v_cvt_pk_fp8_f32 v22, v16, v17
	s_waitcnt vmcnt(24)
	v_mul_f32_e32 v16, 0x41800000, v44
	v_mul_f32_e32 v17, 0x41800000, v45
	v_mov_b32_e32 v23, v3
	v_mul_f32_e32 v18, 0x41800000, v34
	v_mul_f32_e32 v19, 0x41800000, v35
	v_cvt_pk_fp8_f32 v23, v16, v17
	v_cvt_pk_fp8_f32 v20, v18, v19 op_sel:[0,0,1]
	v_mul_f32_e32 v18, 0x41800000, v42
	v_mul_f32_e32 v19, 0x41800000, v43
	v_cvt_pk_fp8_f32 v22, v18, v19 op_sel:[0,0,1]
	v_mul_f32_e32 v16, 0x41800000, v46
	v_mul_f32_e32 v17, 0x41800000, v47
	v_cvt_pk_fp8_f32 v23, v16, v17 op_sel:[0,0,1]
	s_waitcnt vmcnt(23)
	v_mul_f32_e32 v16, 0x41800000, v48
	s_waitcnt vmcnt(22)
	v_mul_f32_e32 v17, 0x41800000, v52
	v_mov_b32_e32 v18, v3
	ds_write_b32 v141, v20 offset:4608
	ds_write_b32 v141, v21 offset:5760
	ds_write_b32 v141, v22 offset:6912
	ds_write_b32 v141, v23 offset:8064
	v_cvt_pk_fp8_f32 v18, v16, v17
	s_waitcnt vmcnt(20)
	v_mul_f32_e32 v17, 0x41800000, v60
	v_mul_f32_e32 v20, 0x41800000, v61
	s_waitcnt vmcnt(16)
	v_mul_f32_e32 v60, 0x41800000, v128
	v_mul_f32_e32 v61, 0x41800000, v129
	v_mov_b32_e32 v128, v3
	v_cvt_pk_fp8_f32 v128, v60, v61
	v_mul_f32_e32 v129, 0x41800000, v130
	v_mul_f32_e32 v130, 0x41800000, v131
	s_waitcnt vmcnt(15)
	v_mul_f32_e32 v124, 0x41800000, v124
	v_cvt_pk_fp8_f32 v128, v129, v130 op_sel:[0,0,1]
	v_mul_f32_e32 v125, 0x41800000, v125
	v_mov_b32_e32 v129, v3
	v_cvt_pk_fp8_f32 v129, v124, v125
	v_mul_f32_e32 v124, 0x41800000, v126
	v_mul_f32_e32 v125, 0x41800000, v127
	s_waitcnt vmcnt(14)
	v_mul_f32_e32 v120, 0x41800000, v120
	v_cvt_pk_fp8_f32 v129, v124, v125 op_sel:[0,0,1]
	v_mul_f32_e32 v121, 0x41800000, v121
	v_mov_b32_e32 v124, v3
	v_cvt_pk_fp8_f32 v124, v120, v121
	v_mul_f32_e32 v120, 0x41800000, v122
	v_mul_f32_e32 v121, 0x41800000, v123
	s_waitcnt vmcnt(13)
	v_mul_f32_e32 v116, 0x41800000, v116
	v_cvt_pk_fp8_f32 v124, v120, v121 op_sel:[0,0,1]
	v_mul_f32_e32 v117, 0x41800000, v117
	v_mov_b32_e32 v120, v3
	v_cvt_pk_fp8_f32 v120, v116, v117
	v_mul_f32_e32 v116, 0x41800000, v118
	v_mul_f32_e32 v117, 0x41800000, v119
	v_mul_f32_e32 v16, 0x41800000, v56
	v_cvt_pk_fp8_f32 v120, v116, v117 op_sel:[0,0,1]
	s_waitcnt vmcnt(12)
	v_mul_f32_e32 v112, 0x41800000, v112
	v_mul_f32_e32 v113, 0x41800000, v113
	v_mov_b32_e32 v116, v3
	v_cvt_pk_fp8_f32 v18, v16, v17 op_sel:[0,0,1]
	v_mul_f32_e32 v16, 0x41800000, v49
	v_mul_f32_e32 v17, 0x41800000, v53
	v_mov_b32_e32 v21, v3
	v_cvt_pk_fp8_f32 v116, v112, v113
	v_cvt_pk_fp8_f32 v21, v16, v17
	v_mul_f32_e32 v16, 0x41800000, v50
	v_mul_f32_e32 v17, 0x41800000, v54
	v_mov_b32_e32 v22, v3
	v_cvt_pk_fp8_f32 v22, v16, v17
	v_mul_f32_e32 v112, 0x41800000, v114
	v_mul_f32_e32 v113, 0x41800000, v115
	v_cvt_pk_fp8_f32 v116, v112, v113 op_sel:[0,0,1]
	s_waitcnt vmcnt(11)
	v_mul_f32_e32 v108, 0x41800000, v108
	v_mul_f32_e32 v109, 0x41800000, v109
	v_mov_b32_e32 v112, v3
	v_mul_f32_e32 v16, 0x41800000, v58
	v_mul_f32_e32 v17, 0x41800000, v62
	v_cvt_pk_fp8_f32 v112, v108, v109
	v_cvt_pk_fp8_f32 v22, v16, v17 op_sel:[0,0,1]
	v_mul_f32_e32 v16, 0x41800000, v51
	v_mul_f32_e32 v17, 0x41800000, v55
	v_mov_b32_e32 v23, v3
	v_cvt_pk_fp8_f32 v23, v16, v17
	v_mul_f32_e32 v4, 0x41800000, v4
	v_mul_f32_e32 v8, 0x41800000, v8
	v_mov_b32_e32 v16, v3
	v_cvt_pk_fp8_f32 v16, v4, v8
	v_mul_f32_e32 v108, 0x41800000, v110
	v_mul_f32_e32 v109, 0x41800000, v111
	v_cvt_pk_fp8_f32 v112, v108, v109 op_sel:[0,0,1]
	s_waitcnt vmcnt(10)
	v_mul_f32_e32 v104, 0x41800000, v104
	v_mul_f32_e32 v105, 0x41800000, v105
	v_mov_b32_e32 v108, v3
	v_cvt_pk_fp8_f32 v108, v104, v105
	s_waitcnt vmcnt(8)
	v_mul_f32_e32 v4, 0x41800000, v64
	v_mul_f32_e32 v8, 0x41800000, v12
	v_cvt_pk_fp8_f32 v16, v4, v8 op_sel:[0,0,1]
	v_mul_f32_e32 v4, 0x41800000, v5
	v_mul_f32_e32 v5, 0x41800000, v9
	v_mov_b32_e32 v8, v3
	v_cvt_pk_fp8_f32 v8, v4, v5
	v_mul_f32_e32 v104, 0x41800000, v106
	v_mul_f32_e32 v105, 0x41800000, v107
	v_cvt_pk_fp8_f32 v108, v104, v105 op_sel:[0,0,1]
	v_mul_f32_e32 v100, 0x41800000, v100
	v_mul_f32_e32 v101, 0x41800000, v101
	v_mov_b32_e32 v104, v3
	v_cvt_pk_fp8_f32 v104, v100, v101
	v_mul_f32_e32 v5, 0x41800000, v65
	v_mul_f32_e32 v9, 0x41800000, v13
	v_cvt_pk_fp8_f32 v8, v5, v9 op_sel:[0,0,1]
	v_mul_f32_e32 v5, 0x41800000, v6
	v_mul_f32_e32 v6, 0x41800000, v10
	v_mov_b32_e32 v12, v3
	v_cvt_pk_fp8_f32 v12, v5, v6
	v_mul_f32_e32 v5, 0x41800000, v7
	v_mul_f32_e32 v6, 0x41800000, v11
	v_mov_b32_e32 v7, v3
	v_mul_f32_e32 v100, 0x41800000, v102
	v_mul_f32_e32 v101, 0x41800000, v103
	v_cvt_pk_fp8_f32 v7, v5, v6
	v_cvt_pk_fp8_f32 v104, v100, v101 op_sel:[0,0,1]
	s_waitcnt vmcnt(7)
	v_mul_f32_e32 v84, 0x41800000, v84
	s_waitcnt vmcnt(6)
	v_mul_f32_e32 v88, 0x41800000, v88
	v_mov_b32_e32 v100, v3
	v_mul_f32_e32 v19, 0x41800000, v57
	v_cvt_pk_fp8_f32 v100, v84, v88
	v_or3_b32 v138, v138, v139, v140
	v_cvt_pk_fp8_f32 v21, v19, v20 op_sel:[0,0,1]
	v_mul_f32_e32 v9, 0x41800000, v66
	v_mul_f32_e32 v10, 0x41800000, v14
	v_add_u32_e32 v139, 0, v138
	v_mul_f32_e32 v19, 0x41800000, v59
	v_mul_f32_e32 v20, 0x41800000, v63
	v_cvt_pk_fp8_f32 v12, v9, v10 op_sel:[0,0,1]
	v_mul_f32_e32 v5, 0x41800000, v67
	v_mul_f32_e32 v6, 0x41800000, v15
	v_cvt_pk_fp8_f32 v23, v19, v20 op_sel:[0,0,1]
	v_add_u32_e32 v4, 0x2400, v139
	v_cvt_pk_fp8_f32 v7, v5, v6 op_sel:[0,0,1]
	s_mov_b32 s6, 0x80000
	s_waitcnt vmcnt(5)
	v_mul_f32_e32 v84, 0x41800000, v92
	s_waitcnt vmcnt(4)
	v_mul_f32_e32 v88, 0x41800000, v96
	ds_write2_b32 v4, v18, v16 offset1:8
	ds_write2_b32 v4, v21, v8 offset0:20 offset1:28
	ds_write2_b32 v4, v22, v12 offset0:40 offset1:48
	ds_write2_b32 v4, v23, v7 offset0:60 offset1:68
	v_add_co_u32_e32 v4, vcc, s6, v136
	v_cvt_pk_fp8_f32 v100, v84, v88 op_sel:[0,0,1]
	v_mul_f32_e32 v84, 0x41800000, v85
	v_mul_f32_e32 v85, 0x41800000, v89
	v_mov_b32_e32 v92, v3
	v_addc_co_u32_e32 v5, vcc, 0, v137, vcc
	s_mov_b32 s6, 0x88000
	v_cvt_pk_fp8_f32 v92, v84, v85
	v_mul_f32_e32 v84, 0x41800000, v86
	v_mul_f32_e32 v85, 0x41800000, v90
	v_mov_b32_e32 v86, v3
	v_add_co_u32_e32 v8, vcc, s6, v136
	v_cvt_pk_fp8_f32 v86, v84, v85
	s_nop 0
	v_addc_co_u32_e32 v9, vcc, 0, v137, vcc
	s_mov_b32 s6, 0x90000
	v_add_co_u32_e32 v12, vcc, s6, v136
	s_mov_b32 s6, 0x98000
	s_nop 0
	v_addc_co_u32_e32 v13, vcc, 0, v137, vcc
	v_mul_f32_e32 v88, 0x41800000, v93
	v_mul_f32_e32 v89, 0x41800000, v97
	v_mul_f32_e32 v84, 0x41800000, v94
	v_mul_f32_e32 v85, 0x41800000, v98
	v_add_co_u32_e32 v16, vcc, s6, v136
	v_cvt_pk_fp8_f32 v92, v88, v89 op_sel:[0,0,1]
	v_cvt_pk_fp8_f32 v86, v84, v85 op_sel:[0,0,1]
	v_mul_f32_e32 v84, 0x41800000, v87
	v_mul_f32_e32 v85, 0x41800000, v91
	v_mov_b32_e32 v89, v3
	v_addc_co_u32_e32 v17, vcc, 0, v137, vcc
	s_mov_b32 s6, 0xa0000
	v_cvt_pk_fp8_f32 v89, v84, v85
	s_waitcnt vmcnt(3)
	v_mul_f32_e32 v68, 0x41800000, v68
	s_waitcnt vmcnt(2)
	v_mul_f32_e32 v80, 0x41800000, v80
	v_mov_b32_e32 v84, v3
	v_add_co_u32_e32 v20, vcc, s6, v136
	v_cvt_pk_fp8_f32 v84, v68, v80
	s_nop 0
	v_addc_co_u32_e32 v21, vcc, 0, v137, vcc
	s_mov_b32 s6, 0xa8000
	v_add_co_u32_e32 v24, vcc, s6, v136
	s_mov_b32 s6, 0xb0000
	s_nop 0
	v_addc_co_u32_e32 v25, vcc, 0, v137, vcc
	s_waitcnt vmcnt(1)
	v_mul_f32_e32 v68, 0x41800000, v72
	s_waitcnt vmcnt(0)
	v_mul_f32_e32 v72, 0x41800000, v76
	v_add_co_u32_e32 v28, vcc, s6, v136
	v_cvt_pk_fp8_f32 v84, v68, v72 op_sel:[0,0,1]
	v_mul_f32_e32 v68, 0x41800000, v69
	v_mul_f32_e32 v69, 0x41800000, v81
	v_mov_b32_e32 v72, v3
	v_addc_co_u32_e32 v29, vcc, 0, v137, vcc
	s_mov_b32 s6, 0xb8000
	v_cvt_pk_fp8_f32 v72, v68, v69
	v_add_co_u32_e32 v32, vcc, s6, v136
	s_mov_b32 s6, 0x81000
	s_nop 0
	v_addc_co_u32_e32 v33, vcc, 0, v137, vcc
	v_add_co_u32_e32 v40, vcc, s6, v134
	v_mul_f32_e32 v69, 0x41800000, v73
	v_mul_f32_e32 v73, 0x41800000, v77
	v_addc_co_u32_e32 v41, vcc, 0, v135, vcc
	s_mov_b32 s6, 0x83000
	v_cvt_pk_fp8_f32 v72, v69, v73 op_sel:[0,0,1]
	v_mul_f32_e32 v69, 0x41800000, v70
	v_mul_f32_e32 v70, 0x41800000, v82
	v_mov_b32_e32 v76, v3
	v_add_co_u32_e32 v48, vcc, s6, v134
	v_cvt_pk_fp8_f32 v76, v69, v70
	v_mul_f32_e32 v69, 0x41800000, v71
	v_mul_f32_e32 v70, 0x41800000, v83
	v_mov_b32_e32 v71, v3
	v_addc_co_u32_e32 v49, vcc, 0, v135, vcc
	s_mov_b32 s6, 0x85000
	v_cvt_pk_fp8_f32 v71, v69, v70
	v_add_co_u32_e32 v56, vcc, s6, v134
	s_mov_b32 s6, 0x87000
	s_nop 0
	v_addc_co_u32_e32 v57, vcc, 0, v135, vcc
	v_mul_f32_e32 v73, 0x41800000, v74
	v_mul_f32_e32 v74, 0x41800000, v78
	v_add_co_u32_e32 v64, vcc, s6, v134
	v_mul_f32_e32 v87, 0x41800000, v95
	v_mul_f32_e32 v88, 0x41800000, v99
	v_cvt_pk_fp8_f32 v76, v73, v74 op_sel:[0,0,1]
	v_mul_f32_e32 v69, 0x41800000, v75
	v_mul_f32_e32 v70, 0x41800000, v79
	v_addc_co_u32_e32 v65, vcc, 0, v135, vcc
	v_cvt_pk_fp8_f32 v89, v87, v88 op_sel:[0,0,1]
	v_add_u32_e32 v68, 0x7000, v139
	v_cvt_pk_fp8_f32 v71, v69, v70 op_sel:[0,0,1]
	s_mov_b32 s6, 0xc0000
	s_waitcnt lgkmcnt(0)
	s_barrier
	global_load_dwordx4 v[4:7], v[4:5], off nt
	s_nop 0
	global_load_dwordx4 v[8:11], v[8:9], off nt
	s_nop 0
	global_load_dwordx4 v[12:15], v[12:13], off nt
	s_nop 0
	global_load_dwordx4 v[16:19], v[16:17], off nt
	s_nop 0
	global_load_dwordx4 v[20:23], v[20:21], off nt
	s_nop 0
	global_load_dwordx4 v[24:27], v[24:25], off nt
	s_nop 0
	global_load_dwordx4 v[28:31], v[28:29], off nt
	s_nop 0
	global_load_dwordx4 v[32:35], v[32:33], off nt
	s_nop 0
	global_load_dwordx4 v[36:39], v[40:41], off offset:-4096 nt
	s_nop 0
	global_load_dwordx4 v[40:43], v[40:41], off nt
	s_nop 0
	global_load_dwordx4 v[44:47], v[48:49], off offset:-4096 nt
	s_nop 0
	global_load_dwordx4 v[48:51], v[48:49], off nt
	s_nop 0
	global_load_dwordx4 v[52:55], v[56:57], off offset:-4096 nt
	s_nop 0
	global_load_dwordx4 v[56:59], v[56:57], off nt
	s_nop 0
	global_load_dwordx4 v[60:63], v[64:65], off offset:-4096 nt
	s_nop 0
	global_load_dwordx4 v[64:67], v[64:65], off nt
	ds_write_b32 v141, v128 offset:19456
	ds_write_b32 v141, v129 offset:20608
	ds_write_b32 v141, v124 offset:21760
	ds_write_b32 v141, v120 offset:22912
	ds_write_b32 v141, v116 offset:24064
	ds_write_b32 v141, v112 offset:25216
	ds_write_b32 v141, v108 offset:26368
	ds_write_b32 v141, v104 offset:27520
	ds_write2_b32 v68, v100, v84 offset1:8
	ds_write2_b32 v68, v92, v72 offset0:20 offset1:28
	ds_write2_b32 v68, v86, v76 offset0:40 offset1:48
	ds_write2_b32 v68, v89, v71 offset0:60 offset1:68
	v_add_co_u32_e32 v68, vcc, s6, v136
	s_mov_b32 s6, 0xc8000
	s_nop 0
	v_addc_co_u32_e32 v69, vcc, 0, v137, vcc
	v_add_co_u32_e32 v72, vcc, s6, v136
	s_mov_b32 s6, 0xd0000
	s_nop 0
	v_addc_co_u32_e32 v73, vcc, 0, v137, vcc
	v_add_co_u32_e32 v76, vcc, s6, v136
	s_mov_b32 s6, 0xd8000
	s_nop 0
	v_addc_co_u32_e32 v77, vcc, 0, v137, vcc
	v_add_co_u32_e32 v80, vcc, s6, v136
	s_mov_b32 s6, 0xe0000
	s_nop 0
	v_addc_co_u32_e32 v81, vcc, 0, v137, vcc
	v_add_co_u32_e32 v84, vcc, s6, v136
	s_mov_b32 s6, 0xe8000
	s_nop 0
	v_addc_co_u32_e32 v85, vcc, 0, v137, vcc
	v_add_co_u32_e32 v88, vcc, s6, v136
	s_mov_b32 s6, 0xf0000
	s_nop 0
	v_addc_co_u32_e32 v89, vcc, 0, v137, vcc
	v_add_co_u32_e32 v92, vcc, s6, v136
	s_mov_b32 s6, 0xf8000
	s_nop 0
	v_addc_co_u32_e32 v93, vcc, 0, v137, vcc
	v_add_co_u32_e32 v96, vcc, s6, v136
	s_mov_b32 s6, 0xc1000
	s_nop 0
	v_addc_co_u32_e32 v97, vcc, 0, v137, vcc
	v_add_co_u32_e32 v104, vcc, s6, v134
	s_mov_b32 s6, 0xc3000
	s_nop 0
	v_addc_co_u32_e32 v105, vcc, 0, v135, vcc
	v_add_co_u32_e32 v112, vcc, s6, v134
	s_mov_b32 s6, 0xc4000
	s_nop 0
	v_addc_co_u32_e32 v113, vcc, 0, v135, vcc
	v_add_co_u32_e32 v116, vcc, s6, v134
	s_waitcnt lgkmcnt(0)
	s_nop 0
	v_addc_co_u32_e32 v117, vcc, 0, v135, vcc
	v_add_co_u32_e32 v120, vcc, 0xc5000, v134
	s_barrier
	s_nop 0
	v_addc_co_u32_e32 v121, vcc, 0, v135, vcc
	v_add_co_u32_e32 v124, vcc, 0xc6000, v134
	s_nop 1
	v_addc_co_u32_e32 v125, vcc, 0, v135, vcc
	v_add_co_u32_e32 v128, vcc, 0xc7000, v134
	global_load_dwordx4 v[68:71], v[68:69], off nt
	s_nop 0
	global_load_dwordx4 v[72:75], v[72:73], off nt
	v_addc_co_u32_e32 v129, vcc, 0, v135, vcc
	global_load_dwordx4 v[76:79], v[76:77], off nt
	s_nop 0
	global_load_dwordx4 v[80:83], v[80:81], off nt
	s_nop 0
	global_load_dwordx4 v[84:87], v[84:85], off nt
	s_nop 0
	global_load_dwordx4 v[88:91], v[88:89], off nt
	s_nop 0
	global_load_dwordx4 v[92:95], v[92:93], off nt
	s_nop 0
	global_load_dwordx4 v[96:99], v[96:97], off nt
	s_nop 0
	global_load_dwordx4 v[100:103], v[104:105], off offset:-4096 nt
	s_nop 0
	global_load_dwordx4 v[104:107], v[104:105], off nt
	s_nop 0
	global_load_dwordx4 v[108:111], v[112:113], off offset:-4096 nt
	s_nop 0
	global_load_dwordx4 v[112:115], v[112:113], off nt
	s_nop 0
	global_load_dwordx4 v[116:119], v[116:117], off nt
	s_nop 0
	global_load_dwordx4 v[120:123], v[120:121], off nt
	s_nop 0
	global_load_dwordx4 v[124:127], v[124:125], off nt
	s_nop 0
	global_load_dwordx4 v[128:131], v[128:129], off nt
	s_mov_b32 s12, 2
	s_mov_b32 s9, 1
	s_branch .LBB0_823

.LBB0_823:
	s_waitcnt vmcnt(31)
	v_mul_f32_e32 v135, 0x41800000, v4
	v_mul_f32_e32 v136, 0x41800000, v5
	v_mov_b32_e32 v140, 0
	v_cvt_pk_fp8_f32 v140, v135, v136
	v_mul_f32_e32 v137, 0x41800000, v6
	v_mul_f32_e32 v139, 0x41800000, v7
	s_mul_i32 s6, s12, 0x4c00
	v_cvt_pk_fp8_f32 v140, v137, v139 op_sel:[0,0,1]
	s_add_i32 s6, s6, 0
	v_add_u32_e32 v134, s6, v1
	s_waitcnt vmcnt(30)
	v_mul_f32_e32 v135, 0x41800000, v8
	ds_write_b32 v134, v140
	v_mul_f32_e32 v136, 0x41800000, v9
	v_mov_b32_e32 v140, 0
	v_cvt_pk_fp8_f32 v140, v135, v136
	v_mul_f32_e32 v137, 0x41800000, v10
	v_mul_f32_e32 v139, 0x41800000, v11
	s_waitcnt vmcnt(29)
	v_mul_f32_e32 v135, 0x41800000, v12
	v_cvt_pk_fp8_f32 v140, v137, v139 op_sel:[0,0,1]
	v_mul_f32_e32 v136, 0x41800000, v13
	v_mul_f32_e32 v137, 0x41800000, v14
	v_mul_f32_e32 v139, 0x41800000, v15
	ds_write_b32 v134, v140 offset:1152
	v_mov_b32_e32 v140, 0
	v_cvt_pk_fp8_f32 v140, v135, v136
	s_waitcnt vmcnt(28)
	v_mul_f32_e32 v135, 0x41800000, v16
	v_mul_f32_e32 v136, 0x41800000, v17
	v_mov_b32_e32 v141, 0
	v_cvt_pk_fp8_f32 v140, v137, v139 op_sel:[0,0,1]
	v_mul_f32_e32 v137, 0x41800000, v18
	v_mul_f32_e32 v139, 0x41800000, v19
	v_mov_b32_e32 v142, 0
	ds_write_b32 v134, v140 offset:2304
	v_mov_b32_e32 v140, 0
	v_cvt_pk_fp8_f32 v140, v135, v136
	s_waitcnt vmcnt(27)
	v_mul_f32_e32 v135, 0x41800000, v20
	v_mul_f32_e32 v136, 0x41800000, v21
	v_mov_b32_e32 v143, 0
	v_cvt_pk_fp8_f32 v140, v137, v139 op_sel:[0,0,1]
	v_mul_f32_e32 v137, 0x41800000, v22
	v_mul_f32_e32 v139, 0x41800000, v23
	v_mov_b32_e32 v144, 0
	ds_write_b32 v134, v140 offset:3456
	v_mov_b32_e32 v140, 0
	v_cvt_pk_fp8_f32 v140, v135, v136
	s_waitcnt vmcnt(26)
	v_mul_f32_e32 v135, 0x41800000, v24
	v_mul_f32_e32 v136, 0x41800000, v25
	s_cmp_gt_u32 s9, 30
	v_cvt_pk_fp8_f32 v140, v137, v139 op_sel:[0,0,1]
	v_mul_f32_e32 v137, 0x41800000, v26
	v_mul_f32_e32 v139, 0x41800000, v27
	ds_write_b32 v134, v140 offset:4608
	v_mov_b32_e32 v140, 0
	v_cvt_pk_fp8_f32 v140, v135, v136
	s_waitcnt vmcnt(25)
	v_mul_f32_e32 v135, 0x41800000, v28
	v_mul_f32_e32 v136, 0x41800000, v29
	v_cvt_pk_fp8_f32 v140, v137, v139 op_sel:[0,0,1]
	v_mul_f32_e32 v137, 0x41800000, v30
	v_mul_f32_e32 v139, 0x41800000, v31
	ds_write_b32 v134, v140 offset:5760
	v_mov_b32_e32 v140, 0
	v_cvt_pk_fp8_f32 v140, v135, v136
	s_waitcnt vmcnt(24)
	v_mul_f32_e32 v135, 0x41800000, v32
	v_mul_f32_e32 v136, 0x41800000, v33
	v_cvt_pk_fp8_f32 v140, v137, v139 op_sel:[0,0,1]
	v_mul_f32_e32 v137, 0x41800000, v34
	v_mul_f32_e32 v139, 0x41800000, v35
	ds_write_b32 v134, v140 offset:6912
	v_mov_b32_e32 v140, 0
	v_cvt_pk_fp8_f32 v140, v135, v136
	s_waitcnt vmcnt(23)
	v_mul_f32_e32 v135, 0x41800000, v36
	s_waitcnt vmcnt(22)
	v_mul_f32_e32 v136, 0x41800000, v40
	v_cvt_pk_fp8_f32 v140, v137, v139 op_sel:[0,0,1]
	s_waitcnt vmcnt(21)
	v_mul_f32_e32 v137, 0x41800000, v44
	s_waitcnt vmcnt(20)
	v_mul_f32_e32 v139, 0x41800000, v48
	ds_write_b32 v134, v140 offset:8064
	v_mov_b32_e32 v140, 0
	v_cvt_pk_fp8_f32 v140, v135, v136
	v_mul_f32_e32 v135, 0x41800000, v37
	v_mul_f32_e32 v136, 0x41800000, v41
	v_cvt_pk_fp8_f32 v141, v135, v136
	v_mul_f32_e32 v135, 0x41800000, v38
	v_mul_f32_e32 v136, 0x41800000, v42
	v_cvt_pk_fp8_f32 v142, v135, v136
	v_mul_f32_e32 v135, 0x41800000, v39
	v_mul_f32_e32 v136, 0x41800000, v43
	v_cvt_pk_fp8_f32 v143, v135, v136
	s_waitcnt vmcnt(19)
	v_mul_f32_e32 v135, 0x41800000, v52
	s_waitcnt vmcnt(18)
	v_mul_f32_e32 v136, 0x41800000, v56
	v_cvt_pk_fp8_f32 v140, v137, v139 op_sel:[0,0,1]
	v_mul_f32_e32 v137, 0x41800000, v45
	v_mul_f32_e32 v139, 0x41800000, v49
	v_cvt_pk_fp8_f32 v144, v135, v136
	v_cvt_pk_fp8_f32 v141, v137, v139 op_sel:[0,0,1]
	v_mul_f32_e32 v137, 0x41800000, v46
	v_mul_f32_e32 v139, 0x41800000, v50
	v_cvt_pk_fp8_f32 v142, v137, v139 op_sel:[0,0,1]
	v_mul_f32_e32 v137, 0x41800000, v47
	v_mul_f32_e32 v139, 0x41800000, v51
	v_cvt_pk_fp8_f32 v143, v137, v139 op_sel:[0,0,1]
	s_waitcnt vmcnt(17)
	v_mul_f32_e32 v137, 0x41800000, v60
	s_waitcnt vmcnt(16)
	v_mul_f32_e32 v139, 0x41800000, v64
	v_cvt_pk_fp8_f32 v144, v137, v139 op_sel:[0,0,1]
	v_add_u32_e32 v134, s6, v138
	v_add_u32_e32 v134, 0x2400, v134
	v_mul_f32_e32 v135, 0x41800000, v53
	ds_write2_b32 v134, v140, v144 offset1:8
	v_mul_f32_e32 v136, 0x41800000, v57
	v_mov_b32_e32 v140, 0
	v_cvt_pk_fp8_f32 v140, v135, v136
	v_mul_f32_e32 v137, 0x41800000, v61
	v_mul_f32_e32 v139, 0x41800000, v65
	v_mul_f32_e32 v135, 0x41800000, v54
	v_cvt_pk_fp8_f32 v140, v137, v139 op_sel:[0,0,1]
	v_mul_f32_e32 v136, 0x41800000, v58
	v_mul_f32_e32 v137, 0x41800000, v62
	v_mul_f32_e32 v139, 0x41800000, v66
	ds_write2_b32 v134, v141, v140 offset0:20 offset1:28
	v_mov_b32_e32 v140, 0
	v_cvt_pk_fp8_f32 v140, v135, v136
	v_mul_f32_e32 v135, 0x41800000, v55
	v_mul_f32_e32 v136, 0x41800000, v59
	s_cselect_b64 s[6:7], -1, 0
	v_cvt_pk_fp8_f32 v140, v137, v139 op_sel:[0,0,1]
	v_mul_f32_e32 v137, 0x41800000, v63
	v_mul_f32_e32 v139, 0x41800000, v67
	s_and_b64 vcc, exec, s[6:7]
	ds_write2_b32 v134, v142, v140 offset0:40 offset1:48
	v_mov_b32_e32 v140, 0
	v_cvt_pk_fp8_f32 v140, v135, v136
	v_cvt_pk_fp8_f32 v140, v137, v139 op_sel:[0,0,1]
	ds_write2_b32 v134, v143, v140 offset0:60 offset1:68
	s_cbranch_vccnz .LBB0_825
	s_add_u32 s13, s0, s95
	s_addc_u32 s14, s1, 0
	s_add_u32 s13, s13, 0x100000
	s_addc_u32 s14, s14, 0
	s_add_u32 s15, s2, s95
	s_addc_u32 s23, s8, 0
	s_add_u32 s34, s15, 0x100000
	s_addc_u32 s23, s23, 0
	s_cmp_lt_u32 s9, 29
	s_cselect_b32 s15, s14, s25
	s_cselect_b32 s14, s13, s3
	v_lshl_add_u64 v[28:29], s[14:15], 0, v[2:3]
	v_add_co_u32_e32 v8, vcc, s90, v28
	s_cselect_b32 s15, s23, s51
	s_nop 0
	v_addc_co_u32_e32 v9, vcc, 0, v29, vcc
	v_add_co_u32_e32 v12, vcc, s37, v28
	s_cselect_b32 s14, s34, s39
	s_nop 0
	v_addc_co_u32_e32 v13, vcc, 0, v29, vcc
	v_add_co_u32_e32 v16, vcc, s38, v28
	v_lshl_add_u64 v[60:61], s[14:15], 0, v[132:133]
	s_nop 0
	v_addc_co_u32_e32 v17, vcc, 0, v29, vcc
	v_add_co_u32_e32 v20, vcc, s53, v28
	global_load_dwordx4 v[4:7], v[28:29], off nt
	s_nop 0
	global_load_dwordx4 v[8:11], v[8:9], off nt
	v_addc_co_u32_e32 v21, vcc, 0, v29, vcc
	v_add_co_u32_e32 v24, vcc, s55, v28
	global_load_dwordx4 v[12:15], v[12:13], off nt
	s_nop 0
	global_load_dwordx4 v[16:19], v[16:17], off nt
	v_addc_co_u32_e32 v25, vcc, 0, v29, vcc
	v_add_co_u32_e32 v30, vcc, s91, v28
	global_load_dwordx4 v[20:23], v[20:21], off nt
	s_nop 0
	global_load_dwordx4 v[24:27], v[24:25], off nt
	v_addc_co_u32_e32 v31, vcc, 0, v29, vcc
	v_add_co_u32_e32 v32, vcc, s93, v28
	s_nop 1
	v_addc_co_u32_e32 v33, vcc, 0, v29, vcc
	v_add_co_u32_e32 v40, vcc, s27, v60
	global_load_dwordx4 v[28:31], v[30:31], off nt
	s_nop 0
	global_load_dwordx4 v[32:35], v[32:33], off nt
	v_addc_co_u32_e32 v41, vcc, 0, v61, vcc
	v_add_co_u32_e32 v44, vcc, 0x2000, v60
	global_load_dwordx4 v[36:39], v[60:61], off nt
	s_nop 0
	global_load_dwordx4 v[40:43], v[40:41], off nt
	v_addc_co_u32_e32 v45, vcc, 0, v61, vcc
	v_add_co_u32_e32 v48, vcc, 0x3000, v60
	s_nop 1
	v_addc_co_u32_e32 v49, vcc, 0, v61, vcc
	v_add_co_u32_e32 v52, vcc, 0x4000, v60
	global_load_dwordx4 v[44:47], v[44:45], off nt
	s_nop 0
	global_load_dwordx4 v[48:51], v[48:49], off nt
	v_addc_co_u32_e32 v53, vcc, 0, v61, vcc
	v_add_co_u32_e32 v56, vcc, 0x5000, v60
	s_nop 1
	v_addc_co_u32_e32 v57, vcc, 0, v61, vcc
	v_add_co_u32_e32 v62, vcc, 0x6000, v60
	global_load_dwordx4 v[52:55], v[52:53], off nt
	s_nop 0
	global_load_dwordx4 v[56:59], v[56:57], off nt
	v_addc_co_u32_e32 v63, vcc, 0, v61, vcc
	v_add_co_u32_e32 v64, vcc, 0x7000, v60
	s_nop 1
	v_addc_co_u32_e32 v65, vcc, 0, v61, vcc
	global_load_dwordx4 v[60:63], v[62:63], off nt
	s_nop 0
	global_load_dwordx4 v[64:67], v[64:65], off nt
.LBB0_825:
	s_waitcnt vmcnt(15)
	v_mul_f32_e32 v135, 0x41800000, v68
	v_mul_f32_e32 v136, 0x41800000, v69
	v_mov_b32_e32 v140, 0
	v_cvt_pk_fp8_f32 v140, v135, v136
	s_add_i32 s13, s12, 1
	s_cmp_lg_u32 s12, 2
	v_mul_f32_e32 v137, 0x41800000, v70
	v_mul_f32_e32 v139, 0x41800000, v71
	s_cselect_b32 s12, s13, 0
	v_cvt_pk_fp8_f32 v140, v137, v139 op_sel:[0,0,1]
	s_mul_i32 s13, s12, 0x4c00
	s_add_i32 s13, s13, 0
	v_add_u32_e32 v134, s13, v1
	s_waitcnt lgkmcnt(0)
	s_barrier
	ds_write_b32 v134, v140
	s_waitcnt vmcnt(14)
	v_mul_f32_e32 v135, 0x41800000, v72
	v_mul_f32_e32 v136, 0x41800000, v73
	v_mov_b32_e32 v140, 0
	v_cvt_pk_fp8_f32 v140, v135, v136
	v_mul_f32_e32 v137, 0x41800000, v74
	v_mul_f32_e32 v139, 0x41800000, v75
	s_waitcnt vmcnt(13)
	v_mul_f32_e32 v135, 0x41800000, v76
	v_cvt_pk_fp8_f32 v140, v137, v139 op_sel:[0,0,1]
	v_mul_f32_e32 v136, 0x41800000, v77
	v_mul_f32_e32 v137, 0x41800000, v78
	v_mul_f32_e32 v139, 0x41800000, v79
	ds_write_b32 v134, v140 offset:1152
	v_mov_b32_e32 v140, 0
	v_cvt_pk_fp8_f32 v140, v135, v136
	s_waitcnt vmcnt(12)
	v_mul_f32_e32 v135, 0x41800000, v80
	v_mul_f32_e32 v136, 0x41800000, v81
	v_mov_b32_e32 v141, 0
	v_cvt_pk_fp8_f32 v140, v137, v139 op_sel:[0,0,1]
	v_mul_f32_e32 v137, 0x41800000, v82
	v_mul_f32_e32 v139, 0x41800000, v83
	v_mov_b32_e32 v142, 0
	ds_write_b32 v134, v140 offset:2304
	v_mov_b32_e32 v140, 0
	v_cvt_pk_fp8_f32 v140, v135, v136
	s_waitcnt vmcnt(11)
	v_mul_f32_e32 v135, 0x41800000, v84
	v_mul_f32_e32 v136, 0x41800000, v85
	v_mov_b32_e32 v143, 0
	v_cvt_pk_fp8_f32 v140, v137, v139 op_sel:[0,0,1]
	v_mul_f32_e32 v137, 0x41800000, v86
	v_mul_f32_e32 v139, 0x41800000, v87
	v_mov_b32_e32 v144, 0
	ds_write_b32 v134, v140 offset:3456
	v_mov_b32_e32 v140, 0
	v_cvt_pk_fp8_f32 v140, v135, v136
	s_waitcnt vmcnt(10)
	v_mul_f32_e32 v135, 0x41800000, v88
	v_mul_f32_e32 v136, 0x41800000, v89
	s_cmp_gt_u32 s9, 29
	v_cvt_pk_fp8_f32 v140, v137, v139 op_sel:[0,0,1]
	v_mul_f32_e32 v137, 0x41800000, v90
	v_mul_f32_e32 v139, 0x41800000, v91
	ds_write_b32 v134, v140 offset:4608
	v_mov_b32_e32 v140, 0
	v_cvt_pk_fp8_f32 v140, v135, v136
	s_waitcnt vmcnt(9)
	v_mul_f32_e32 v135, 0x41800000, v92
	v_mul_f32_e32 v136, 0x41800000, v93
	v_cvt_pk_fp8_f32 v140, v137, v139 op_sel:[0,0,1]
	v_mul_f32_e32 v137, 0x41800000, v94
	v_mul_f32_e32 v139, 0x41800000, v95
	ds_write_b32 v134, v140 offset:5760
	v_mov_b32_e32 v140, 0
	v_cvt_pk_fp8_f32 v140, v135, v136
	s_waitcnt vmcnt(8)
	v_mul_f32_e32 v135, 0x41800000, v96
	v_mul_f32_e32 v136, 0x41800000, v97
	v_cvt_pk_fp8_f32 v140, v137, v139 op_sel:[0,0,1]
	v_mul_f32_e32 v137, 0x41800000, v98
	v_mul_f32_e32 v139, 0x41800000, v99
	ds_write_b32 v134, v140 offset:6912
	v_mov_b32_e32 v140, 0
	v_cvt_pk_fp8_f32 v140, v135, v136
	s_waitcnt vmcnt(7)
	v_mul_f32_e32 v135, 0x41800000, v100
	s_waitcnt vmcnt(6)
	v_mul_f32_e32 v136, 0x41800000, v104
	v_cvt_pk_fp8_f32 v140, v137, v139 op_sel:[0,0,1]
	s_waitcnt vmcnt(5)
	v_mul_f32_e32 v137, 0x41800000, v108
	s_waitcnt vmcnt(4)
	v_mul_f32_e32 v139, 0x41800000, v112
	ds_write_b32 v134, v140 offset:8064
	v_mov_b32_e32 v140, 0
	v_cvt_pk_fp8_f32 v140, v135, v136
	v_mul_f32_e32 v135, 0x41800000, v101
	v_mul_f32_e32 v136, 0x41800000, v105
	v_cvt_pk_fp8_f32 v141, v135, v136
	v_mul_f32_e32 v135, 0x41800000, v102
	v_mul_f32_e32 v136, 0x41800000, v106
	v_cvt_pk_fp8_f32 v142, v135, v136
	v_mul_f32_e32 v135, 0x41800000, v103
	v_mul_f32_e32 v136, 0x41800000, v107
	v_cvt_pk_fp8_f32 v143, v135, v136
	s_waitcnt vmcnt(3)
	v_mul_f32_e32 v135, 0x41800000, v116
	s_waitcnt vmcnt(2)
	v_mul_f32_e32 v136, 0x41800000, v120
	v_cvt_pk_fp8_f32 v140, v137, v139 op_sel:[0,0,1]
	v_mul_f32_e32 v137, 0x41800000, v109
	v_mul_f32_e32 v139, 0x41800000, v113
	v_cvt_pk_fp8_f32 v144, v135, v136
	v_cvt_pk_fp8_f32 v141, v137, v139 op_sel:[0,0,1]
	v_mul_f32_e32 v137, 0x41800000, v110
	v_mul_f32_e32 v139, 0x41800000, v114
	v_cvt_pk_fp8_f32 v142, v137, v139 op_sel:[0,0,1]
	v_mul_f32_e32 v137, 0x41800000, v111
	v_mul_f32_e32 v139, 0x41800000, v115
	v_cvt_pk_fp8_f32 v143, v137, v139 op_sel:[0,0,1]
	s_waitcnt vmcnt(1)
	v_mul_f32_e32 v137, 0x41800000, v124
	s_waitcnt vmcnt(0)
	v_mul_f32_e32 v139, 0x41800000, v128
	v_cvt_pk_fp8_f32 v144, v137, v139 op_sel:[0,0,1]
	v_add_u32_e32 v134, s13, v138
	v_add_u32_e32 v134, 0x2400, v134
	v_mul_f32_e32 v135, 0x41800000, v117
	ds_write2_b32 v134, v140, v144 offset1:8
	v_mul_f32_e32 v136, 0x41800000, v121
	v_mov_b32_e32 v140, 0
	v_cvt_pk_fp8_f32 v140, v135, v136
	v_mul_f32_e32 v137, 0x41800000, v125
	v_mul_f32_e32 v139, 0x41800000, v129
	v_mul_f32_e32 v135, 0x41800000, v118
	v_cvt_pk_fp8_f32 v140, v137, v139 op_sel:[0,0,1]
	v_mul_f32_e32 v136, 0x41800000, v122
	v_mul_f32_e32 v137, 0x41800000, v126
	v_mul_f32_e32 v139, 0x41800000, v130
	ds_write2_b32 v134, v141, v140 offset0:20 offset1:28
	v_mov_b32_e32 v140, 0
	v_cvt_pk_fp8_f32 v140, v135, v136
	v_mul_f32_e32 v135, 0x41800000, v119
	v_mul_f32_e32 v136, 0x41800000, v123
	v_cvt_pk_fp8_f32 v140, v137, v139 op_sel:[0,0,1]
	v_mul_f32_e32 v137, 0x41800000, v127
	v_mul_f32_e32 v139, 0x41800000, v131
	ds_write2_b32 v134, v142, v140 offset0:40 offset1:48
	v_mov_b32_e32 v140, 0
	v_cvt_pk_fp8_f32 v140, v135, v136
	v_cvt_pk_fp8_f32 v140, v137, v139 op_sel:[0,0,1]
	ds_write2_b32 v134, v143, v140 offset0:60 offset1:68
	s_cbranch_scc1 .LBB0_822
	s_add_u32 s13, s0, s95
	s_addc_u32 s14, s1, 0
	s_add_u32 s13, s13, 0x140000
	s_addc_u32 s14, s14, 0
	s_add_u32 s15, s2, s95
	s_addc_u32 s23, s8, 0
	s_add_u32 s34, s15, 0x140000
	s_addc_u32 s23, s23, 0
	s_cmp_lt_u32 s9, 28
	s_cselect_b32 s15, s14, s25
	s_cselect_b32 s14, s13, s3
	v_lshl_add_u64 v[92:93], s[14:15], 0, v[2:3]
	v_add_co_u32_e32 v72, vcc, s90, v92
	s_cselect_b32 s15, s23, s51
	s_nop 0
	v_addc_co_u32_e32 v73, vcc, 0, v93, vcc
	v_add_co_u32_e32 v76, vcc, s37, v92
	s_cselect_b32 s14, s34, s39
	s_nop 0
	v_addc_co_u32_e32 v77, vcc, 0, v93, vcc
	v_add_co_u32_e32 v80, vcc, s38, v92
	v_lshl_add_u64 v[124:125], s[14:15], 0, v[132:133]
	s_nop 0
	v_addc_co_u32_e32 v81, vcc, 0, v93, vcc
	v_add_co_u32_e32 v84, vcc, s53, v92
	global_load_dwordx4 v[68:71], v[92:93], off nt
	s_nop 0
	global_load_dwordx4 v[72:75], v[72:73], off nt
	v_addc_co_u32_e32 v85, vcc, 0, v93, vcc
	v_add_co_u32_e32 v88, vcc, s55, v92
	global_load_dwordx4 v[76:79], v[76:77], off nt
	s_nop 0
	global_load_dwordx4 v[80:83], v[80:81], off nt
	v_addc_co_u32_e32 v89, vcc, 0, v93, vcc
	v_add_co_u32_e32 v94, vcc, s91, v92
	global_load_dwordx4 v[84:87], v[84:85], off nt
	s_nop 0
	global_load_dwordx4 v[88:91], v[88:89], off nt
	v_addc_co_u32_e32 v95, vcc, 0, v93, vcc
	v_add_co_u32_e32 v96, vcc, s93, v92
	s_nop 1
	v_addc_co_u32_e32 v97, vcc, 0, v93, vcc
	v_add_co_u32_e32 v104, vcc, s27, v124
	global_load_dwordx4 v[92:95], v[94:95], off nt
	s_nop 0
	global_load_dwordx4 v[96:99], v[96:97], off nt
	v_addc_co_u32_e32 v105, vcc, 0, v125, vcc
	v_add_co_u32_e32 v108, vcc, 0x2000, v124
	global_load_dwordx4 v[100:103], v[124:125], off nt
	s_nop 0
	global_load_dwordx4 v[104:107], v[104:105], off nt
	v_addc_co_u32_e32 v109, vcc, 0, v125, vcc
	v_add_co_u32_e32 v112, vcc, 0x3000, v124
	s_nop 1
	v_addc_co_u32_e32 v113, vcc, 0, v125, vcc
	v_add_co_u32_e32 v116, vcc, 0x4000, v124
	global_load_dwordx4 v[108:111], v[108:109], off nt
	s_nop 0
	global_load_dwordx4 v[112:115], v[112:113], off nt
	v_addc_co_u32_e32 v117, vcc, 0, v125, vcc
	v_add_co_u32_e32 v120, vcc, 0x5000, v124
	s_nop 1
	v_addc_co_u32_e32 v121, vcc, 0, v125, vcc
	v_add_co_u32_e32 v126, vcc, 0x6000, v124
	global_load_dwordx4 v[116:119], v[116:117], off nt
	s_nop 0
	global_load_dwordx4 v[120:123], v[120:121], off nt
	v_addc_co_u32_e32 v127, vcc, 0, v125, vcc
	v_add_co_u32_e32 v128, vcc, 0x7000, v124
	s_nop 1
	v_addc_co_u32_e32 v129, vcc, 0, v125, vcc
	global_load_dwordx4 v[124:127], v[126:127], off nt
	s_nop 0
	global_load_dwordx4 v[128:131], v[128:129], off nt
	s_branch .LBB0_822
